# K3: 3-deep K ring in attention, first 4 K fragments of next S tile pre-read before the step barrier
# speedup vs baseline: 1.0188x; 1.0006x over previous
.LBB0_275:
	s_or_b64 exec, exec, s[0:1]
	s_ashr_i32 s69, s63, 6
	s_and_b32 s27, s69, 3
	s_lshl_b32 s14, s62, 7
	s_add_i32 s0, s14, s61
	s_lshl_b32 s15, s27, 5
	v_and_b32_e32 v199, 31, v10
	s_or_b32 s0, s15, s0
	v_or_b32_e32 v12, s0, v199
	s_ashr_i32 s26, s63, 8
	v_ashrrev_i32_e32 v13, 31, v12
	v_lshlrev_b64 v[2:3], 11, v[12:13]
	s_lshl_b32 s0, s26, 6
	v_bfe_u32 v198, v10, 5, 1
	v_lshl_add_u64 v[2:3], s[44:45], 0, v[2:3]
	s_ashr_i32 s1, s0, 31
	v_lshl_add_u64 v[2:3], s[0:1], 1, v[2:3]
	v_lshlrev_b32_e32 v0, 4, v198
	v_bfe_u32 v4, v10, 4, 2
	s_lshl_b32 s1, s69, 3
	v_lshl_add_u64 v[2:3], v[2:3], 0, v[0:1]
	v_or_b32_e32 v0, s1, v4
	global_load_dword v200, v1, s[4:5] offset:256
	global_load_dword v201, v1, s[4:5] offset:2812
	global_load_dwordx4 v[130:133], v[2:3], off
	global_load_dwordx4 v[134:137], v[2:3], off offset:32
	global_load_dwordx4 v[138:141], v[2:3], off offset:64
	global_load_dwordx4 v[142:145], v[2:3], off offset:96
	v_add_u32_e32 v2, s61, v0
	v_bitop3_b32 v6, s1, v10, v4 bitop3:0x36
	v_ashrrev_i32_e32 v3, 31, v2
	v_lshlrev_b64 v[2:3], 11, v[2:3]
	v_lshlrev_b32_e32 v0, 4, v6
	v_bfe_u32 v5, v10, 3, 3
	v_lshl_add_u64 v[2:3], s[46:47], 0, v[2:3]
	v_and_b32_e32 v0, 0xf0, v0
	v_lshl_add_u64 v[188:189], v[2:3], 0, v[0:1]
	v_or_b32_e32 v2, s67, v5
	v_lshl_add_u32 v2, s69, 4, v2
	s_lshl_b32 s0, s69, 1
	v_xor_b32_e32 v0, v4, v10
	v_ashrrev_i32_e32 v3, 31, v2
	v_lshlrev_b64 v[2:3], 15, v[2:3]
	v_lshlrev_b32_e32 v0, 4, v0
	s_or_b32 s0, s0, 1
	v_lshl_add_u64 v[2:3], s[50:51], 0, v[2:3]
	v_and_b32_e32 v0, 0x70, v0
	s_lshl_b32 s1, s0, 2
	v_lshl_add_u64 v[190:191], v[2:3], 0, v[0:1]
	v_or_b32_e32 v0, s1, v4
	v_add_u32_e32 v2, s61, v0
	v_bitop3_b32 v4, s1, v10, v4 bitop3:0x36
	v_ashrrev_i32_e32 v3, 31, v2
	v_lshlrev_b64 v[2:3], 11, v[2:3]
	v_lshlrev_b32_e32 v0, 4, v4
	v_lshl_add_u64 v[2:3], s[46:47], 0, v[2:3]
	v_and_b32_e32 v0, 0xf0, v0
	v_lshl_add_u64 v[192:193], v[2:3], 0, v[0:1]
	v_lshl_or_b32 v0, s0, 3, v5
	v_lshrrev_b32_e32 v2, 1, v0
	v_xor_b32_e32 v4, v2, v10
	v_add_u32_e32 v2, s67, v0
	v_ashrrev_i32_e32 v3, 31, v2
	v_lshlrev_b64 v[2:3], 15, v[2:3]
	v_lshlrev_b32_e32 v0, 4, v4
	s_lshl_b32 s0, s69, 11
	v_lshl_add_u64 v[2:3], s[50:51], 0, v[2:3]
	v_and_b32_e32 v0, 0x70, v0
	s_add_i32 s70, s0, 0
	s_mov_b32 s29, s23
	v_lshl_add_u64 v[194:195], v[2:3], 0, v[0:1]
	v_lshl_add_u64 v[2:3], v[188:189], 0, s[28:29]
	s_mov_b32 m0, s70
	s_add_i32 s71, s70, 0x8000
	global_load_lds_dwordx4 v[2:3], off
	v_lshl_add_u64 v[2:3], v[192:193], 0, s[28:29]
	s_add_i32 s29, s70, 0x400
	s_mov_b32 m0, s29
	s_lshl_b64 s[0:1], s[34:35], 1
	global_load_lds_dwordx4 v[2:3], off
	v_lshl_add_u64 v[2:3], v[190:191], 0, s[0:1]
	s_mov_b32 m0, s71
	s_add_i32 s72, s70, 0x8400
	global_load_lds_dwordx4 v[2:3], off
	v_lshl_add_u64 v[2:3], v[194:195], 0, s[0:1]
	s_mov_b32 m0, s72
	s_add_i32 s73, s70, 0x4000
	s_mov_b32 s31, s23
	global_load_lds_dwordx4 v[2:3], off
	v_lshl_add_u64 v[2:3], v[188:189], 0, s[30:31]
	s_mov_b32 m0, s73
	v_and_b32_e32 v0, 19, v10
	global_load_lds_dwordx4 v[2:3], off
	v_lshl_add_u64 v[2:3], v[192:193], 0, s[30:31]
	s_add_i32 s31, s70, 0x4400
	s_mov_b32 m0, s31
	v_lshrrev_b32_e32 v11, 1, v10
	global_load_lds_dwordx4 v[2:3], off
	s_add_i32 s22, s30, 0x20000
	s_and_b32 s22, s22, 0x7e0000
	s_add_i32 m0, s70, 0x14000
	v_lshl_add_u64 v[2:3], v[188:189], 0, s[22:23]
	global_load_lds_dwordx4 v[2:3], off
	v_lshl_add_u64 v[2:3], v[192:193], 0, s[22:23]
	s_add_i32 m0, s70, 0x14400
	s_nop 0
	global_load_lds_dwordx4 v[2:3], off
	v_lshlrev_b32_e32 v2, 1, v10
	v_and_or_b32 v17, v2, 8, v0
	v_and_b32_e32 v18, 4, v11
	v_or_b32_e32 v2, v17, v18
	v_lshl_or_b32 v14, s26, 3, v198
	v_lshlrev_b32_e32 v0, 8, v2
	v_bitop3_b32 v2, v2, v14, 15 bitop3:0x6c
	s_or_b32 s14, s15, s14
	v_lshl_add_u32 v2, v2, 4, v0
	s_add_i32 s74, s14, 0xffffffa5
	v_add_u32_e32 v202, 0, v2
	s_cmp_gt_i32 s65, s74
	s_waitcnt vmcnt(0)
	s_waitcnt vmcnt(0) lgkmcnt(0)
	s_barrier
	ds_read_b128 v[6:9], v202
	ds_read_b128 v[2:5], v202 offset:8192
	s_cselect_b64 s[0:1], -1, 0
	s_add_i32 s75, s14, 0x7a
	s_cmp_lt_i32 s34, s75
	s_cselect_b64 s[40:41], -1, 0
	s_and_b64 s[0:1], s[0:1], s[40:41]
	s_andn2_b64 vcc, exec, s[0:1]
	s_mov_b64 s[0:1], -1
	s_cbranch_vccz .LBB0_277
	s_waitcnt lgkmcnt(1)
	v_mfma_f32_32x32x16_bf16 v[66:81], v[6:9], v[130:133], 0
	s_mov_b64 s[0:1], 0
	s_waitcnt lgkmcnt(0)
	v_mfma_f32_32x32x16_bf16 v[82:97], v[2:5], v[130:133], 0

.LBB0_279:
	v_bitop3_b32 v17, v17, 15, v18 bitop3:0xc8
	s_waitcnt lgkmcnt(0)
	v_bitop3_b32 v2, v14, v17, 2 bitop3:0x36
	v_lshl_add_u32 v2, v2, 4, v0
	v_add_u32_e32 v204, 0, v2
	ds_read_b128 v[2:5], v204
	ds_read_b128 v[6:9], v204 offset:8192
	v_and_b32_e32 v203, 63, v10
	v_and_b32_e32 v10, 7, v11
	v_lshlrev_b64 v[186:187], 10, v[12:13]
	s_waitcnt lgkmcnt(1)
	v_mfma_f32_32x32x16_bf16 v[66:81], v[2:5], v[134:137], v[66:81]
	v_bitop3_b32 v2, v14, v17, 4 bitop3:0x36
	v_lshl_add_u32 v2, v2, 4, v0
	v_add_u32_e32 v205, 0, v2
	ds_read_b128 v[2:5], v205
	v_bitop3_b32 v19, v198, v11, 7 bitop3:0x78
	v_bitop3_b32 v20, v198, v10, 2 bitop3:0x36
	v_bitop3_b32 v21, v198, v10, 4 bitop3:0x36
	s_waitcnt lgkmcnt(1)
	v_mfma_f32_32x32x16_bf16 v[82:97], v[6:9], v[134:137], v[82:97]
	v_bitop3_b32 v6, v14, v17, 6 bitop3:0x36
	v_lshl_add_u32 v0, v6, 4, v0
	ds_read_b128 v[6:9], v205 offset:8192
	v_add_u32_e32 v206, 0, v0
	v_bitop3_b32 v14, v198, v10, 6 bitop3:0x36
	v_lshlrev_b32_e32 v18, 7, v199
	v_sub_u32_e32 v0, v15, v16
	s_waitcnt lgkmcnt(1)
	v_mfma_f32_32x32x16_bf16 v[66:81], v[2:5], v[138:141], v[66:81]
	ds_read_b128 v[2:5], v206
	ds_read_b128 v[10:13], v206 offset:8192
	v_lshl_or_b32 v16, v19, 4, v18
	v_lshl_or_b32 v17, v20, 4, v18
	v_lshl_or_b32 v19, v21, 4, v18
	v_lshl_or_b32 v18, v14, 4, v18
	v_mov_b32_e32 v14, v1
	v_mov_b32_e32 v15, v1
	s_waitcnt lgkmcnt(2)
	v_mfma_f32_32x32x16_bf16 v[82:97], v[6:9], v[138:141], v[82:97]
	v_lshl_add_u32 v207, v0, 2, s68
	v_mov_b32_e32 v0, v1
	v_mov_b32_e32 v6, v1
	v_mov_b32_e32 v7, v1
	v_mov_b32_e32 v8, v1
	v_mov_b32_e32 v9, v1
	v_add_u32_e32 v210, 0, v19
	s_waitcnt lgkmcnt(1)
	v_mfma_f32_32x32x16_bf16 v[66:81], v[2:5], v[142:145], v[66:81]
	v_mov_b32_e32 v2, v1
	v_mov_b32_e32 v3, v1
	v_mov_b32_e32 v4, v1
	v_mov_b32_e32 v5, v1
	v_add_u32_e32 v212, 0, v18
	v_add_u32_e32 v208, 0, v16
	v_add_u32_e32 v209, 0, v17
	s_waitcnt lgkmcnt(0)
	v_mfma_f32_32x32x16_bf16 v[82:97], v[10:13], v[142:145], v[82:97]
	v_add_u32_e32 v202, 0x4000, v202
	v_add_u32_e32 v204, 0x4000, v204
	v_add_u32_e32 v205, 0x4000, v205
	v_add_u32_e32 v206, 0x4000, v206
	s_mov_b32 s100, 0
	ds_read_b128 v[174:177], v202
	ds_read_b128 v[170:173], v202 offset:8192
	ds_read_b128 v[166:169], v204
	ds_read_b128 v[162:165], v204 offset:8192
	v_mov_b32_e32 v10, v1
	v_mov_b32_e32 v11, v1
	v_mov_b32_e32 v12, v1
	v_mov_b32_e32 v13, v1
	v_mov_b64_e32 v[64:65], v[14:15]
	v_mov_b64_e32 v[48:49], v[14:15]
	v_mov_b64_e32 v[32:33], v[14:15]
	v_mov_b64_e32 v[62:63], v[12:13]
	v_mov_b64_e32 v[60:61], v[10:11]
	v_mov_b64_e32 v[58:59], v[8:9]
	v_mov_b64_e32 v[56:57], v[6:7]
	v_mov_b64_e32 v[54:55], v[4:5]
	v_mov_b64_e32 v[52:53], v[2:3]
	v_mov_b64_e32 v[50:51], v[0:1]
	v_mov_b64_e32 v[46:47], v[12:13]
	v_mov_b64_e32 v[44:45], v[10:11]
	v_mov_b64_e32 v[42:43], v[8:9]
	v_mov_b64_e32 v[40:41], v[6:7]
	v_mov_b64_e32 v[38:39], v[4:5]
	v_mov_b64_e32 v[36:37], v[2:3]
	v_mov_b64_e32 v[34:35], v[0:1]
	v_mov_b64_e32 v[30:31], v[12:13]
	v_mov_b64_e32 v[28:29], v[10:11]
	v_mov_b64_e32 v[26:27], v[8:9]
	v_mov_b64_e32 v[24:25], v[6:7]
	v_mov_b64_e32 v[22:23], v[4:5]
	v_mov_b64_e32 v[20:21], v[2:3]
	v_mov_b64_e32 v[18:19], v[0:1]
	v_mov_b64_e32 v[16:17], v[14:15]
	s_mov_b32 s14, 1
	v_mov_b32_e32 v213, 0
	s_mov_b32 s76, -2
	s_mov_b32 s77, s82
	s_mov_b32 s78, s66
	v_mov_b64_e32 v[14:15], v[12:13]
	v_mov_b64_e32 v[12:13], v[10:11]
	v_mov_b64_e32 v[10:11], v[8:9]
	v_mov_b64_e32 v[8:9], v[6:7]
	v_mov_b64_e32 v[6:7], v[4:5]
	v_mov_b64_e32 v[4:5], v[2:3]
	v_mov_b64_e32 v[2:3], v[0:1]
	v_exp_f32_e32 v66, v66
	v_exp_f32_e32 v67, v67
	v_exp_f32_e32 v68, v68
	v_exp_f32_e32 v69, v69
	v_exp_f32_e32 v70, v70
	v_exp_f32_e32 v71, v71
	v_exp_f32_e32 v72, v72
	v_exp_f32_e32 v73, v73
	v_exp_f32_e32 v74, v74
	v_exp_f32_e32 v75, v75
	v_exp_f32_e32 v76, v76
	v_exp_f32_e32 v77, v77
	v_exp_f32_e32 v78, v78
	v_exp_f32_e32 v79, v79
	v_exp_f32_e32 v80, v80
	v_exp_f32_e32 v81, v81
	v_exp_f32_e32 v82, v82
	v_exp_f32_e32 v83, v83
	v_exp_f32_e32 v84, v84
	v_exp_f32_e32 v85, v85
	v_exp_f32_e32 v86, v86
	v_exp_f32_e32 v87, v87
	v_exp_f32_e32 v88, v88
	v_exp_f32_e32 v89, v89
	v_exp_f32_e32 v90, v90
	v_exp_f32_e32 v91, v91
	v_exp_f32_e32 v92, v92
	v_exp_f32_e32 v93, v93
	v_exp_f32_e32 v94, v94
	v_exp_f32_e32 v95, v95
	v_exp_f32_e32 v96, v96
	v_exp_f32_e32 v97, v97
	s_waitcnt lgkmcnt(0)
	s_barrier
	s_branch .LBB0_281
.LBB0_280:
	s_waitcnt lgkmcnt(5)
	v_mfma_f32_32x32x16_bf16 v[66:81], v[166:169], v[134:137], v[66:81]
	v_add_f32_e32 v174, v114, v115
	v_add_f32_e32 v175, v116, v117
	v_add_f32_e32 v176, v118, v119
	v_add_f32_e32 v177, v120, v121
	v_add_f32_e32 v174, v174, v122
	s_waitcnt lgkmcnt(4)
	v_mfma_f32_32x32x16_bf16 v[82:97], v[162:165], v[134:137], v[82:97]
	v_add_f32_e32 v175, v175, v123
	v_add_f32_e32 v176, v176, v124
	v_add_f32_e32 v177, v177, v125
	v_add_f32_e32 v174, v174, v126
	v_add_f32_e32 v175, v175, v127
	s_waitcnt lgkmcnt(3)
	v_mfma_f32_32x32x16_bf16 v[66:81], v[158:161], v[138:141], v[66:81]
	v_add_f32_e32 v176, v176, v128
	v_add_f32_e32 v177, v177, v129
	v_add_f32_e32 v174, v174, v98
	v_add_f32_e32 v175, v175, v99
	v_add_f32_e32 v176, v176, v100
	s_waitcnt lgkmcnt(2)
	v_mfma_f32_32x32x16_bf16 v[82:97], v[154:157], v[138:141], v[82:97]
	v_add_f32_e32 v177, v177, v101
	v_add_f32_e32 v174, v174, v102
	v_add_f32_e32 v175, v175, v103
	v_add_f32_e32 v176, v176, v104
	v_add_f32_e32 v177, v177, v105
	s_waitcnt lgkmcnt(1)
	v_mfma_f32_32x32x16_bf16 v[66:81], v[150:153], v[142:145], v[66:81]
	v_add_f32_e32 v174, v174, v106
	v_add_f32_e32 v175, v175, v107
	v_add_f32_e32 v176, v176, v108
	v_add_f32_e32 v177, v177, v109
	s_waitcnt lgkmcnt(0)
	v_mfma_f32_32x32x16_bf16 v[82:97], v[146:149], v[142:145], v[82:97]
	v_add_f32_e32 v174, v174, v110
	v_add_f32_e32 v175, v175, v111
	v_add_f32_e32 v176, v176, v112
	v_add_f32_e32 v177, v177, v113
	v_add_f32_e32 v174, v174, v175
	v_add_f32_e32 v176, v176, v177
	v_cvt_pk_bf16_f32 v113, v112, v113
	v_cvt_pk_bf16_f32 v112, v110, v111
	v_cvt_pk_bf16_f32 v111, v108, v109
	v_cvt_pk_bf16_f32 v110, v106, v107
	v_add_f32_e32 v174, v174, v176
	v_cvt_pk_bf16_f32 v109, v104, v105
	v_cvt_pk_bf16_f32 v108, v102, v103
	v_cvt_pk_bf16_f32 v107, v100, v101
	v_cvt_pk_bf16_f32 v106, v98, v99
	v_cvt_pk_bf16_f32 v98, v114, v115
	v_cvt_pk_bf16_f32 v99, v116, v117
	v_cvt_pk_bf16_f32 v100, v118, v119
	v_cvt_pk_bf16_f32 v101, v120, v121
	v_cvt_pk_bf16_f32 v102, v122, v123
	v_cvt_pk_bf16_f32 v103, v124, v125
	v_cvt_pk_bf16_f32 v104, v126, v127
	v_cvt_pk_bf16_f32 v105, v128, v129
	v_add_f32_e32 v213, v174, v0
	ds_read_b128 v[114:117], v208 offset:49152
	ds_read_b128 v[118:121], v208 offset:53248
	ds_read_b128 v[122:125], v208 offset:57344
	ds_read_b128 v[126:129], v208 offset:61440
	ds_read_b128 v[150:153], v209 offset:53248
	ds_read_b128 v[146:149], v209 offset:49152
	ds_read_b128 v[154:157], v209 offset:57344
	ds_read_b128 v[158:161], v209 offset:61440
	s_add_i32 s0, s77, 0x10000
	s_and_b32 s0, s0, 0x3f0000
	s_lshl_b32 s22, s0, 1
	s_add_i32 m0, s70, s100
	v_lshl_add_u64 v[164:165], v[188:189], 0, s[22:23]
	global_load_lds_dwordx4 v[164:165], off
	v_lshl_add_u64 v[164:165], v[192:193], 0, s[22:23]
	s_add_i32 m0, s29, s100
	s_lshl_b32 s22, s15, 1
	global_load_lds_dwordx4 v[164:165], off
	v_lshl_add_u64 v[164:165], v[190:191], 0, s[22:23]
	s_mov_b32 m0, s71
	global_load_lds_dwordx4 v[164:165], off
	v_lshl_add_u64 v[164:165], v[194:195], 0, s[22:23]
	s_mov_b32 m0, s72
	s_nop 0
	global_load_lds_dwordx4 v[164:165], off
	s_waitcnt lgkmcnt(0)
	v_mfma_f32_32x32x16_bf16 v[50:65], v[98:101], v[114:117], v[50:65]
	ds_read_b128 v[114:117], v210 offset:53248
	v_exp_f32_e32 v66, v66
	v_exp_f32_e32 v67, v67
	v_mfma_f32_32x32x16_bf16 v[34:49], v[98:101], v[118:121], v[34:49]
	ds_read_b128 v[118:121], v210 offset:57344
	v_exp_f32_e32 v68, v68
	v_exp_f32_e32 v69, v69
	v_mfma_f32_32x32x16_bf16 v[18:33], v[98:101], v[122:125], v[18:33]
	ds_read_b128 v[122:125], v210 offset:61440
	v_exp_f32_e32 v70, v70
	v_exp_f32_e32 v71, v71
	v_mfma_f32_32x32x16_bf16 v[2:17], v[98:101], v[126:129], v[2:17]
	ds_read_b128 v[98:101], v210 offset:49152
	v_exp_f32_e32 v72, v72
	v_exp_f32_e32 v73, v73
	v_mfma_f32_32x32x16_bf16 v[50:65], v[102:105], v[146:149], v[50:65]
	ds_read_b128 v[126:129], v212 offset:53248
	v_exp_f32_e32 v74, v74
	v_exp_f32_e32 v75, v75
	v_mfma_f32_32x32x16_bf16 v[34:49], v[102:105], v[150:153], v[34:49]
	ds_read_b128 v[146:149], v212 offset:57344
	v_exp_f32_e32 v76, v76
	v_exp_f32_e32 v77, v77
	v_mfma_f32_32x32x16_bf16 v[18:33], v[102:105], v[154:157], v[18:33]
	ds_read_b128 v[150:153], v212 offset:61440
	v_exp_f32_e32 v78, v78
	v_exp_f32_e32 v79, v79
	v_mfma_f32_32x32x16_bf16 v[2:17], v[102:105], v[158:161], v[2:17]
	ds_read_b128 v[102:105], v212 offset:49152
	v_exp_f32_e32 v80, v80
	v_exp_f32_e32 v81, v81
	s_add_u32 s101, s100, 0x4000
	s_cmp_eq_u32 s101, 0x8000
	s_cselect_b32 s101, 0x14000, s101
	s_cmp_eq_u32 s101, 0x18000
	s_cselect_b32 s101, 0, s101
	s_lshl_b32 s22, s101, 1
	s_add_u32 s22, s22, s100
	s_sub_u32 s22, 0x18000, s22
	s_mov_b32 s100, s101
	s_waitcnt lgkmcnt(0)
	v_mfma_f32_32x32x16_bf16 v[50:65], v[106:109], v[98:101], v[50:65]
	v_add_u32_e32 v202, s22, v202
	v_add_u32_e32 v204, s22, v204
	v_exp_f32_e32 v82, v82
	v_exp_f32_e32 v83, v83
	v_mfma_f32_32x32x16_bf16 v[34:49], v[106:109], v[114:117], v[34:49]
	ds_read_b128 v[174:177], v202
	ds_read_b128 v[170:173], v202 offset:8192
	v_exp_f32_e32 v84, v84
	v_exp_f32_e32 v85, v85
	v_mfma_f32_32x32x16_bf16 v[18:33], v[106:109], v[118:121], v[18:33]
	ds_read_b128 v[166:169], v204
	ds_read_b128 v[162:165], v204 offset:8192
	v_exp_f32_e32 v86, v86
	v_exp_f32_e32 v87, v87
	v_mfma_f32_32x32x16_bf16 v[2:17], v[106:109], v[122:125], v[2:17]
	v_add_u32_e32 v205, s22, v205
	v_add_u32_e32 v206, s22, v206
	v_exp_f32_e32 v88, v88
	v_exp_f32_e32 v89, v89
	v_mfma_f32_32x32x16_bf16 v[50:65], v[110:113], v[102:105], v[50:65]
	v_exp_f32_e32 v90, v90
	v_exp_f32_e32 v91, v91
	v_mfma_f32_32x32x16_bf16 v[34:49], v[110:113], v[126:129], v[34:49]
	v_exp_f32_e32 v92, v92
	v_exp_f32_e32 v93, v93
	v_mfma_f32_32x32x16_bf16 v[18:33], v[110:113], v[146:149], v[18:33]
	v_exp_f32_e32 v94, v94
	v_exp_f32_e32 v95, v95
	v_mfma_f32_32x32x16_bf16 v[2:17], v[110:113], v[150:153], v[2:17]
	v_exp_f32_e32 v96, v96
	v_exp_f32_e32 v97, v97
	s_waitcnt vmcnt(0)
	s_add_i32 s76, s76, 2
	s_add_i32 s77, s77, 0x20000
	s_cmp_gt_u32 s76, 61
	s_waitcnt vmcnt(0)
	s_waitcnt lgkmcnt(0)
	s_barrier
	s_cbranch_scc1 .LBB0_295

.LBB0_284:
	ds_read_b128 v[158:161], v205
	ds_read_b128 v[154:157], v205 offset:8192
	ds_read_b128 v[150:153], v206
	ds_read_b128 v[146:149], v206 offset:8192
	s_add_i32 s0, s78, 64
	s_and_b32 s80, s0, 0xfc0
	s_or_b32 s0, s80, 63
	s_cmp_gt_i32 s0, s74
	s_cselect_b64 s[40:41], -1, 0
	s_cmp_lt_i32 s80, s75
	s_cselect_b64 s[0:1], -1, 0
	s_and_b64 s[14:15], s[40:41], s[0:1]
	s_andn2_b64 vcc, exec, s[14:15]
	s_mov_b64 s[14:15], -1
	s_cbranch_vccz .LBB0_286
	s_waitcnt lgkmcnt(7)
	v_mfma_f32_32x32x16_bf16 v[114:129], v[174:177], v[130:133], 0
	s_mov_b64 s[14:15], 0
	s_waitcnt lgkmcnt(6)
	v_mfma_f32_32x32x16_bf16 v[98:113], v[170:173], v[130:133], 0

.LBB0_288:
	s_waitcnt lgkmcnt(5)
	v_mfma_f32_32x32x16_bf16 v[114:129], v[166:169], v[134:137], v[114:129]
	v_add_f32_e32 v174, v66, v67
	v_add_f32_e32 v175, v68, v69
	v_add_f32_e32 v176, v70, v71
	v_add_f32_e32 v177, v72, v73
	v_add_f32_e32 v174, v174, v74
	s_waitcnt lgkmcnt(4)
	v_mfma_f32_32x32x16_bf16 v[98:113], v[162:165], v[134:137], v[98:113]
	v_add_f32_e32 v175, v175, v75
	v_add_f32_e32 v176, v176, v76
	v_add_f32_e32 v177, v177, v77
	v_add_f32_e32 v174, v174, v78
	v_add_f32_e32 v175, v175, v79
	s_waitcnt lgkmcnt(3)
	v_mfma_f32_32x32x16_bf16 v[114:129], v[158:161], v[138:141], v[114:129]
	v_add_f32_e32 v176, v176, v80
	v_add_f32_e32 v177, v177, v81
	v_add_f32_e32 v174, v174, v82
	v_add_f32_e32 v175, v175, v83
	v_add_f32_e32 v176, v176, v84
	s_waitcnt lgkmcnt(2)
	v_mfma_f32_32x32x16_bf16 v[98:113], v[154:157], v[138:141], v[98:113]
	v_add_f32_e32 v177, v177, v85
	v_add_f32_e32 v174, v174, v86
	v_add_f32_e32 v175, v175, v87
	v_add_f32_e32 v176, v176, v88
	v_add_f32_e32 v177, v177, v89
	s_waitcnt lgkmcnt(1)
	v_mfma_f32_32x32x16_bf16 v[114:129], v[150:153], v[142:145], v[114:129]
	v_add_f32_e32 v174, v174, v90
	v_add_f32_e32 v175, v175, v91
	v_add_f32_e32 v176, v176, v92
	v_add_f32_e32 v177, v177, v93
	s_waitcnt lgkmcnt(0)
	v_mfma_f32_32x32x16_bf16 v[98:113], v[146:149], v[142:145], v[98:113]
	v_add_f32_e32 v174, v174, v94
	v_add_f32_e32 v175, v175, v95
	v_add_f32_e32 v176, v176, v96
	v_add_f32_e32 v177, v177, v97
	v_add_f32_e32 v174, v174, v175
	v_add_f32_e32 v176, v176, v177
	v_cvt_pk_bf16_f32 v66, v66, v67
	v_cvt_pk_bf16_f32 v67, v68, v69
	v_cvt_pk_bf16_f32 v68, v70, v71
	v_cvt_pk_bf16_f32 v69, v72, v73
	v_add_f32_e32 v174, v174, v176
	v_cvt_pk_bf16_f32 v70, v74, v75
	v_cvt_pk_bf16_f32 v71, v76, v77
	v_cvt_pk_bf16_f32 v72, v78, v79
	v_cvt_pk_bf16_f32 v73, v80, v81
	v_cvt_pk_bf16_f32 v74, v82, v83
	v_cvt_pk_bf16_f32 v75, v84, v85
	v_cvt_pk_bf16_f32 v76, v86, v87
	v_cvt_pk_bf16_f32 v77, v88, v89
	v_cvt_pk_bf16_f32 v78, v90, v91
	v_cvt_pk_bf16_f32 v79, v92, v93
	v_cvt_pk_bf16_f32 v80, v94, v95
	v_cvt_pk_bf16_f32 v81, v96, v97
	v_add_f32_e32 v0, v174, v213
	ds_read_b128 v[82:85], v208 offset:32768
	ds_read_b128 v[86:89], v208 offset:36864
	ds_read_b128 v[90:93], v208 offset:40960
	ds_read_b128 v[94:97], v208 offset:45056
	ds_read_b128 v[146:149], v209 offset:32768
	ds_read_b128 v[150:153], v209 offset:36864
	ds_read_b128 v[154:157], v209 offset:40960
	ds_read_b128 v[158:161], v209 offset:45056
	s_and_b32 s14, s77, 0x3f0000
	s_lshl_b32 s22, s14, 1
	s_add_i32 m0, s70, s100
	v_lshl_add_u64 v[164:165], v[188:189], 0, s[22:23]
	global_load_lds_dwordx4 v[164:165], off
	v_lshl_add_u64 v[164:165], v[192:193], 0, s[22:23]
	s_add_i32 m0, s29, s100
	s_lshl_b32 s22, s80, 1
	global_load_lds_dwordx4 v[164:165], off
	v_lshl_add_u64 v[164:165], v[190:191], 0, s[22:23]
	s_add_i32 m0, s70, 0xc000
	global_load_lds_dwordx4 v[164:165], off
	v_lshl_add_u64 v[164:165], v[194:195], 0, s[22:23]
	s_add_i32 m0, s70, 0xc400
	s_nop 0
	global_load_lds_dwordx4 v[164:165], off
	s_waitcnt lgkmcnt(0)
	v_mfma_f32_32x32x16_bf16 v[50:65], v[66:69], v[82:85], v[50:65]
	ds_read_b128 v[82:85], v210 offset:32768
	v_exp_f32_e32 v114, v114
	v_exp_f32_e32 v115, v115
	v_mfma_f32_32x32x16_bf16 v[34:49], v[66:69], v[86:89], v[34:49]
	ds_read_b128 v[86:89], v210 offset:36864
	v_exp_f32_e32 v116, v116
	v_exp_f32_e32 v117, v117
	v_mfma_f32_32x32x16_bf16 v[18:33], v[66:69], v[90:93], v[18:33]
	ds_read_b128 v[90:93], v210 offset:40960
	v_exp_f32_e32 v118, v118
	v_exp_f32_e32 v119, v119
	v_mfma_f32_32x32x16_bf16 v[2:17], v[66:69], v[94:97], v[2:17]
	ds_read_b128 v[66:69], v210 offset:45056
	v_exp_f32_e32 v120, v120
	v_exp_f32_e32 v121, v121
	v_mfma_f32_32x32x16_bf16 v[50:65], v[70:73], v[146:149], v[50:65]
	ds_read_b128 v[94:97], v212 offset:32768
	v_exp_f32_e32 v122, v122
	v_exp_f32_e32 v123, v123
	v_mfma_f32_32x32x16_bf16 v[34:49], v[70:73], v[150:153], v[34:49]
	ds_read_b128 v[146:149], v212 offset:36864
	v_exp_f32_e32 v124, v124
	v_exp_f32_e32 v125, v125
	v_mfma_f32_32x32x16_bf16 v[18:33], v[70:73], v[154:157], v[18:33]
	ds_read_b128 v[150:153], v212 offset:40960
	v_exp_f32_e32 v126, v126
	v_exp_f32_e32 v127, v127
	v_mfma_f32_32x32x16_bf16 v[2:17], v[70:73], v[158:161], v[2:17]
	ds_read_b128 v[70:73], v212 offset:45056
	v_exp_f32_e32 v128, v128
	v_exp_f32_e32 v129, v129
	s_add_u32 s101, s100, 0x4000
	s_cmp_eq_u32 s101, 0x8000
	s_cselect_b32 s101, 0x14000, s101
	s_cmp_eq_u32 s101, 0x18000
	s_cselect_b32 s101, 0, s101
	s_lshl_b32 s22, s101, 1
	s_add_u32 s22, s22, s100
	s_sub_u32 s22, 0x18000, s22
	s_mov_b32 s100, s101
	s_waitcnt lgkmcnt(0)
	v_mfma_f32_32x32x16_bf16 v[50:65], v[74:77], v[82:85], v[50:65]
	v_add_u32_e32 v202, s22, v202
	v_add_u32_e32 v204, s22, v204
	v_exp_f32_e32 v98, v98
	v_exp_f32_e32 v99, v99
	v_mfma_f32_32x32x16_bf16 v[34:49], v[74:77], v[86:89], v[34:49]
	ds_read_b128 v[174:177], v202
	ds_read_b128 v[170:173], v202 offset:8192
	v_exp_f32_e32 v100, v100
	v_exp_f32_e32 v101, v101
	v_mfma_f32_32x32x16_bf16 v[18:33], v[74:77], v[90:93], v[18:33]
	ds_read_b128 v[166:169], v204
	ds_read_b128 v[162:165], v204 offset:8192
	v_exp_f32_e32 v102, v102
	v_exp_f32_e32 v103, v103
	v_mfma_f32_32x32x16_bf16 v[2:17], v[74:77], v[66:69], v[2:17]
	v_add_u32_e32 v205, s22, v205
	v_add_u32_e32 v206, s22, v206
	v_exp_f32_e32 v104, v104
	v_exp_f32_e32 v105, v105
	v_mfma_f32_32x32x16_bf16 v[50:65], v[78:81], v[94:97], v[50:65]
	v_exp_f32_e32 v106, v106
	v_exp_f32_e32 v107, v107
	v_mfma_f32_32x32x16_bf16 v[34:49], v[78:81], v[146:149], v[34:49]
	v_exp_f32_e32 v108, v108
	v_exp_f32_e32 v109, v109
	v_mfma_f32_32x32x16_bf16 v[18:33], v[78:81], v[150:153], v[18:33]
	v_exp_f32_e32 v110, v110
	v_exp_f32_e32 v111, v111
	v_mfma_f32_32x32x16_bf16 v[2:17], v[78:81], v[70:73], v[2:17]
	v_exp_f32_e32 v112, v112
	v_exp_f32_e32 v113, v113
	s_and_b64 s[0:1], s[0:1], exec
	s_waitcnt vmcnt(0)
	s_cselect_b32 s14, 1, 2
	s_and_b64 s[0:1], s[40:41], exec
	s_cselect_b32 s14, s14, 0
	s_cmp_eq_u32 s14, s79
	s_waitcnt vmcnt(0)
	s_waitcnt lgkmcnt(0)
	s_barrier
	s_cbranch_scc1 .LBB0_290
	s_cmp_eq_u32 s79, 0
	s_cselect_b64 vcc, -1, 0
	s_cmp_eq_u32 s79, 2
	s_cselect_b64 s[0:1], -1, 0
	v_cndmask_b32_e64 v66, 0, v201, s[0:1]
	s_cmp_eq_u32 s14, 2
	v_cndmask_b32_e32 v66, v66, v200, vcc
	s_cselect_b64 vcc, -1, 0
	v_cndmask_b32_e32 v67, 0, v201, vcc
	v_cndmask_b32_e64 v67, v200, v67, s[40:41]
	v_sub_f32_e32 v66, v66, v67
	v_exp_f32_e32 v66, v66
	s_nop 0
	v_pk_mul_f32 v[64:65], v[66:67], v[64:65] op_sel_hi:[0,1]
	v_pk_mul_f32 v[62:63], v[66:67], v[62:63] op_sel_hi:[0,1]
	v_pk_mul_f32 v[60:61], v[66:67], v[60:61] op_sel_hi:[0,1]
	v_pk_mul_f32 v[58:59], v[66:67], v[58:59] op_sel_hi:[0,1]
	v_pk_mul_f32 v[56:57], v[66:67], v[56:57] op_sel_hi:[0,1]
	v_pk_mul_f32 v[54:55], v[66:67], v[54:55] op_sel_hi:[0,1]
	v_pk_mul_f32 v[52:53], v[66:67], v[52:53] op_sel_hi:[0,1]
	v_pk_mul_f32 v[50:51], v[66:67], v[50:51] op_sel_hi:[0,1]
	v_pk_mul_f32 v[48:49], v[66:67], v[48:49] op_sel_hi:[0,1]
	v_pk_mul_f32 v[46:47], v[66:67], v[46:47] op_sel_hi:[0,1]
	v_pk_mul_f32 v[44:45], v[66:67], v[44:45] op_sel_hi:[0,1]
	v_pk_mul_f32 v[42:43], v[66:67], v[42:43] op_sel_hi:[0,1]
	v_pk_mul_f32 v[40:41], v[66:67], v[40:41] op_sel_hi:[0,1]
	v_pk_mul_f32 v[38:39], v[66:67], v[38:39] op_sel_hi:[0,1]
	v_pk_mul_f32 v[36:37], v[66:67], v[36:37] op_sel_hi:[0,1]
	v_pk_mul_f32 v[34:35], v[66:67], v[34:35] op_sel_hi:[0,1]
	v_pk_mul_f32 v[32:33], v[66:67], v[32:33] op_sel_hi:[0,1]
	v_pk_mul_f32 v[30:31], v[66:67], v[30:31] op_sel_hi:[0,1]
	v_pk_mul_f32 v[28:29], v[66:67], v[28:29] op_sel_hi:[0,1]
	v_pk_mul_f32 v[26:27], v[66:67], v[26:27] op_sel_hi:[0,1]
	v_pk_mul_f32 v[24:25], v[66:67], v[24:25] op_sel_hi:[0,1]
	v_pk_mul_f32 v[22:23], v[66:67], v[22:23] op_sel_hi:[0,1]
	v_pk_mul_f32 v[20:21], v[66:67], v[20:21] op_sel_hi:[0,1]
	v_pk_mul_f32 v[18:19], v[66:67], v[18:19] op_sel_hi:[0,1]
	v_pk_mul_f32 v[16:17], v[66:67], v[16:17] op_sel_hi:[0,1]
	v_pk_mul_f32 v[14:15], v[66:67], v[14:15] op_sel_hi:[0,1]
	v_pk_mul_f32 v[12:13], v[66:67], v[12:13] op_sel_hi:[0,1]
	v_pk_mul_f32 v[10:11], v[66:67], v[10:11] op_sel_hi:[0,1]
	v_pk_mul_f32 v[8:9], v[66:67], v[8:9] op_sel_hi:[0,1]
	v_pk_mul_f32 v[6:7], v[66:67], v[6:7] op_sel_hi:[0,1]
	v_pk_mul_f32 v[4:5], v[66:67], v[4:5] op_sel_hi:[0,1]
	v_pk_mul_f32 v[2:3], v[66:67], v[2:3] op_sel_hi:[0,1]
	v_mul_f32_e32 v0, v0, v66
	s_branch .LBB0_291

.LBB0_291:
	ds_read_b128 v[158:161], v205
	ds_read_b128 v[154:157], v205 offset:8192
	ds_read_b128 v[150:153], v206
	ds_read_b128 v[146:149], v206 offset:8192
	s_addk_i32 s78, 0x80
	s_and_b32 s15, s78, 0xf80
	s_or_b32 s0, s15, 63
	s_cmp_gt_i32 s0, s74
	s_cselect_b64 s[0:1], -1, 0
	s_cmp_lt_i32 s15, s75
	s_cselect_b64 s[40:41], -1, 0
	s_and_b64 s[0:1], s[0:1], s[40:41]
	s_andn2_b64 vcc, exec, s[0:1]
	s_mov_b64 s[0:1], -1
	s_cbranch_vccz .LBB0_293
	s_waitcnt lgkmcnt(7)
	v_mfma_f32_32x32x16_bf16 v[66:81], v[174:177], v[130:133], 0
	s_mov_b64 s[0:1], 0
	s_waitcnt lgkmcnt(6)
	v_mfma_f32_32x32x16_bf16 v[82:97], v[170:173], v[130:133], 0

	.amdhsa_kernel _Z10fwd_kernel4Args
		.amdhsa_group_segment_fixed_size 0
		.amdhsa_private_segment_fixed_size 0
		.amdhsa_kernarg_size 400
		.amdhsa_user_sgpr_count 2
		.amdhsa_user_sgpr_dispatch_ptr 0
		.amdhsa_user_sgpr_queue_ptr 0
		.amdhsa_user_sgpr_kernarg_segment_ptr 1
		.amdhsa_user_sgpr_dispatch_id 0
		.amdhsa_user_sgpr_kernarg_preload_length 0
		.amdhsa_user_sgpr_kernarg_preload_offset 0
		.amdhsa_user_sgpr_private_segment_size 0
		.amdhsa_uses_dynamic_stack 0
		.amdhsa_enable_private_segment 0
		.amdhsa_system_sgpr_workgroup_id_x 1
		.amdhsa_system_sgpr_workgroup_id_y 0
		.amdhsa_system_sgpr_workgroup_id_z 0
		.amdhsa_system_sgpr_workgroup_info 0
		.amdhsa_system_vgpr_workitem_id 2
		.amdhsa_next_free_vgpr 256
		.amdhsa_next_free_sgpr 102
		.amdhsa_accum_offset 256
		.amdhsa_reserve_vcc 1
		.amdhsa_float_round_mode_32 0
		.amdhsa_float_round_mode_16_64 0
		.amdhsa_float_denorm_mode_32 3
		.amdhsa_float_denorm_mode_16_64 3
		.amdhsa_dx10_clamp 1
		.amdhsa_ieee_mode 1
		.amdhsa_fp16_overflow 0
		.amdhsa_tg_split 0
		.amdhsa_exception_fp_ieee_invalid_op 0
		.amdhsa_exception_fp_denorm_src 0
		.amdhsa_exception_fp_ieee_div_zero 0
		.amdhsa_exception_fp_ieee_overflow 0
		.amdhsa_exception_fp_ieee_underflow 0
		.amdhsa_exception_fp_ieee_inexact 0
		.amdhsa_exception_int_div_zero 0
	.end_amdhsa_kernel

amdhsa.kernels:
  - .agpr_count:     0
    .args:
      - .offset:         0
        .size:           144
        .value_kind:     by_value
      - .offset:         144
        .size:           4
        .value_kind:     hidden_block_count_x
      - .offset:         148
        .size:           4
        .value_kind:     hidden_block_count_y
      - .offset:         152
        .size:           4
        .value_kind:     hidden_block_count_z
      - .offset:         156
        .size:           2
        .value_kind:     hidden_group_size_x
      - .offset:         158
        .size:           2
        .value_kind:     hidden_group_size_y
      - .offset:         160
        .size:           2
        .value_kind:     hidden_group_size_z
      - .offset:         162
        .size:           2
        .value_kind:     hidden_remainder_x
      - .offset:         164
        .size:           2
        .value_kind:     hidden_remainder_y
      - .offset:         166
        .size:           2
        .value_kind:     hidden_remainder_z
      - .offset:         184
        .size:           8
        .value_kind:     hidden_global_offset_x
      - .offset:         192
        .size:           8
        .value_kind:     hidden_global_offset_y
      - .offset:         200
        .size:           8
        .value_kind:     hidden_global_offset_z
      - .offset:         208
        .size:           2
        .value_kind:     hidden_grid_dims
      - .offset:         232
        .size:           8
        .value_kind:     hidden_multigrid_sync_arg
      - .offset:         264
        .size:           4
        .value_kind:     hidden_dynamic_lds_size
    .group_segment_fixed_size: 0
    .kernarg_segment_align: 8
    .kernarg_segment_size: 400
    .language:       OpenCL C
    .language_version:
      - 2
      - 0
    .max_flat_workgroup_size: 512
    .name:           _Z10fwd_kernel4Args
    .private_segment_fixed_size: 0
    .sgpr_count:     108
    .sgpr_spill_count: 173
    .symbol:         _Z10fwd_kernel4Args.kd
    .uniform_work_group_size: 1
    .uses_dynamic_stack: false
    .vgpr_count:     256
    .vgpr_spill_count: 0
    .wavefront_size: 64
